# v112 + the seven GEMM K-loop heads aligned to 64 bytes (.p2align 6)
# baseline (speedup 1.0000x reference)
.LBB0_299:
	s_ashr_i32 s21, s20, 31
	s_lshl_b64 s[24:25], s[20:21], 19
	s_add_u32 s21, s28, s24
	s_addc_u32 s55, s29, s25
	s_ashr_i32 s24, s20, 5
	s_ashr_i32 s25, s24, 31
	s_lshl_b64 s[24:25], s[24:25], 11
	s_add_u32 s24, s21, s24
	v_mov_b32_e32 v127, 0
	s_addc_u32 s25, s55, s25
	s_andn2_b64 vcc, exec, s[16:17]
	v_mov_b32_e32 v126, v127
	v_mov_b32_e32 v125, v127
	v_mov_b32_e32 v124, v127
	v_mov_b32_e32 v123, v127
	v_mov_b32_e32 v122, v127
	v_mov_b32_e32 v121, v127
	v_mov_b32_e32 v120, v127
	v_mov_b32_e32 v111, v127
	v_mov_b32_e32 v110, v127
	v_mov_b32_e32 v109, v127
	v_mov_b32_e32 v108, v127
	v_mov_b32_e32 v107, v127
	v_mov_b32_e32 v106, v127
	v_mov_b32_e32 v105, v127
	v_mov_b32_e32 v104, v127
	v_mov_b32_e32 v95, v127
	v_mov_b32_e32 v94, v127
	v_mov_b32_e32 v93, v127
	v_mov_b32_e32 v92, v127
	v_mov_b32_e32 v91, v127
	v_mov_b32_e32 v90, v127
	v_mov_b32_e32 v89, v127
	v_mov_b32_e32 v88, v127
	v_mov_b32_e32 v79, v127
	v_mov_b32_e32 v78, v127
	v_mov_b32_e32 v77, v127
	v_mov_b32_e32 v76, v127
	v_mov_b32_e32 v75, v127
	v_mov_b32_e32 v74, v127
	v_mov_b32_e32 v73, v127
	v_mov_b32_e32 v72, v127
	v_mov_b32_e32 v119, v127
	v_mov_b32_e32 v118, v127
	v_mov_b32_e32 v117, v127
	v_mov_b32_e32 v116, v127
	v_mov_b32_e32 v115, v127
	v_mov_b32_e32 v114, v127
	v_mov_b32_e32 v113, v127
	v_mov_b32_e32 v112, v127
	v_mov_b32_e32 v103, v127
	v_mov_b32_e32 v102, v127
	v_mov_b32_e32 v101, v127
	v_mov_b32_e32 v100, v127
	v_mov_b32_e32 v99, v127
	v_mov_b32_e32 v98, v127
	v_mov_b32_e32 v97, v127
	v_mov_b32_e32 v96, v127
	v_mov_b32_e32 v87, v127
	v_mov_b32_e32 v86, v127
	v_mov_b32_e32 v85, v127
	v_mov_b32_e32 v84, v127
	v_mov_b32_e32 v83, v127
	v_mov_b32_e32 v82, v127
	v_mov_b32_e32 v81, v127
	v_mov_b32_e32 v80, v127
	v_mov_b32_e32 v71, v127
	v_mov_b32_e32 v70, v127
	v_mov_b32_e32 v69, v127
	v_mov_b32_e32 v68, v127
	v_mov_b32_e32 v67, v127
	v_mov_b32_e32 v66, v127
	v_mov_b32_e32 v65, v127
	v_mov_b32_e32 v64, v127
	v_mov_b32_e32 v63, v127
	v_mov_b32_e32 v62, v127
	v_mov_b32_e32 v61, v127
	v_mov_b32_e32 v60, v127
	v_mov_b32_e32 v59, v127
	v_mov_b32_e32 v58, v127
	v_mov_b32_e32 v57, v127
	v_mov_b32_e32 v56, v127
	v_mov_b32_e32 v47, v127
	v_mov_b32_e32 v46, v127
	v_mov_b32_e32 v45, v127
	v_mov_b32_e32 v44, v127
	v_mov_b32_e32 v43, v127
	v_mov_b32_e32 v42, v127
	v_mov_b32_e32 v41, v127
	v_mov_b32_e32 v40, v127
	v_mov_b32_e32 v31, v127
	v_mov_b32_e32 v30, v127
	v_mov_b32_e32 v29, v127
	v_mov_b32_e32 v28, v127
	v_mov_b32_e32 v27, v127
	v_mov_b32_e32 v26, v127
	v_mov_b32_e32 v25, v127
	v_mov_b32_e32 v24, v127
	v_mov_b32_e32 v15, v127
	v_mov_b32_e32 v14, v127
	v_mov_b32_e32 v13, v127
	v_mov_b32_e32 v12, v127
	v_mov_b32_e32 v11, v127
	v_mov_b32_e32 v10, v127
	v_mov_b32_e32 v9, v127
	v_mov_b32_e32 v8, v127
	v_mov_b32_e32 v55, v127
	v_mov_b32_e32 v54, v127
	v_mov_b32_e32 v53, v127
	v_mov_b32_e32 v52, v127
	v_mov_b32_e32 v51, v127
	v_mov_b32_e32 v50, v127
	v_mov_b32_e32 v49, v127
	v_mov_b32_e32 v48, v127
	v_mov_b32_e32 v39, v127
	v_mov_b32_e32 v38, v127
	v_mov_b32_e32 v37, v127
	v_mov_b32_e32 v36, v127
	v_mov_b32_e32 v35, v127
	v_mov_b32_e32 v34, v127
	v_mov_b32_e32 v33, v127
	v_mov_b32_e32 v32, v127
	v_mov_b32_e32 v23, v127
	v_mov_b32_e32 v22, v127
	v_mov_b32_e32 v21, v127
	v_mov_b32_e32 v20, v127
	v_mov_b32_e32 v19, v127
	v_mov_b32_e32 v18, v127
	v_mov_b32_e32 v17, v127
	v_mov_b32_e32 v16, v127
	v_mov_b32_e32 v7, v127
	v_mov_b32_e32 v6, v127
	v_mov_b32_e32 v5, v127
	v_mov_b32_e32 v4, v127
	v_mov_b32_e32 v3, v127
	v_mov_b32_e32 v2, v127
	v_mov_b32_e32 v1, v127
	v_mov_b32_e32 v0, v127
	s_cbranch_vccnz .LBB0_303
	s_and_b64 s[8:9], s[8:9], exec
	s_cselect_b32 s21, s25, s1
	s_cselect_b32 s55, s24, s0
	s_add_u32 s8, s0, 0x40080
	s_addc_u32 s9, s1, 0
	s_add_u32 s26, s26, 0x100
	v_mov_b32_e32 v0, 0
	s_addc_u32 s27, s27, 0
	s_mov_b32 s0, 0
	v_mov_b32_e32 v1, v0
	v_mov_b32_e32 v2, v0
	v_mov_b32_e32 v3, v0
	v_mov_b32_e32 v4, v0
	v_mov_b32_e32 v5, v0
	v_mov_b32_e32 v6, v0
	v_mov_b32_e32 v7, v0
	v_mov_b32_e32 v16, v0
	v_mov_b32_e32 v17, v0
	v_mov_b32_e32 v18, v0
	v_mov_b32_e32 v19, v0
	v_mov_b32_e32 v20, v0
	v_mov_b32_e32 v21, v0
	v_mov_b32_e32 v22, v0
	v_mov_b32_e32 v23, v0
	v_mov_b32_e32 v32, v0
	v_mov_b32_e32 v33, v0
	v_mov_b32_e32 v34, v0
	v_mov_b32_e32 v35, v0
	v_mov_b32_e32 v36, v0
	v_mov_b32_e32 v37, v0
	v_mov_b32_e32 v38, v0
	v_mov_b32_e32 v39, v0
	v_mov_b32_e32 v48, v0
	v_mov_b32_e32 v49, v0
	v_mov_b32_e32 v50, v0
	v_mov_b32_e32 v51, v0
	v_mov_b32_e32 v52, v0
	v_mov_b32_e32 v53, v0
	v_mov_b32_e32 v54, v0
	v_mov_b32_e32 v55, v0
	v_mov_b32_e32 v8, v0
	v_mov_b32_e32 v9, v0
	v_mov_b32_e32 v10, v0
	v_mov_b32_e32 v11, v0
	v_mov_b32_e32 v12, v0
	v_mov_b32_e32 v13, v0
	v_mov_b32_e32 v14, v0
	v_mov_b32_e32 v15, v0
	v_mov_b32_e32 v24, v0
	v_mov_b32_e32 v25, v0
	v_mov_b32_e32 v26, v0
	v_mov_b32_e32 v27, v0
	v_mov_b32_e32 v28, v0
	v_mov_b32_e32 v29, v0
	v_mov_b32_e32 v30, v0
	v_mov_b32_e32 v31, v0
	v_mov_b32_e32 v40, v0
	v_mov_b32_e32 v41, v0
	v_mov_b32_e32 v42, v0
	v_mov_b32_e32 v43, v0
	v_mov_b32_e32 v44, v0
	v_mov_b32_e32 v45, v0
	v_mov_b32_e32 v46, v0
	v_mov_b32_e32 v47, v0
	v_mov_b32_e32 v56, v0
	v_mov_b32_e32 v57, v0
	v_mov_b32_e32 v58, v0
	v_mov_b32_e32 v59, v0
	v_mov_b32_e32 v60, v0
	v_mov_b32_e32 v61, v0
	v_mov_b32_e32 v62, v0
	v_mov_b32_e32 v63, v0
	v_mov_b32_e32 v64, v0
	v_mov_b32_e32 v65, v0
	v_mov_b32_e32 v66, v0
	v_mov_b32_e32 v67, v0
	v_mov_b32_e32 v68, v0
	v_mov_b32_e32 v69, v0
	v_mov_b32_e32 v70, v0
	v_mov_b32_e32 v71, v0
	v_mov_b32_e32 v80, v0
	v_mov_b32_e32 v81, v0
	v_mov_b32_e32 v82, v0
	v_mov_b32_e32 v83, v0
	v_mov_b32_e32 v84, v0
	v_mov_b32_e32 v85, v0
	v_mov_b32_e32 v86, v0
	v_mov_b32_e32 v87, v0
	v_mov_b32_e32 v96, v0
	v_mov_b32_e32 v97, v0
	v_mov_b32_e32 v98, v0
	v_mov_b32_e32 v99, v0
	v_mov_b32_e32 v100, v0
	v_mov_b32_e32 v101, v0
	v_mov_b32_e32 v102, v0
	v_mov_b32_e32 v103, v0
	v_mov_b32_e32 v112, v0
	v_mov_b32_e32 v113, v0
	v_mov_b32_e32 v114, v0
	v_mov_b32_e32 v115, v0
	v_mov_b32_e32 v116, v0
	v_mov_b32_e32 v117, v0
	v_mov_b32_e32 v118, v0
	v_mov_b32_e32 v119, v0
	v_mov_b32_e32 v72, v0
	v_mov_b32_e32 v73, v0
	v_mov_b32_e32 v74, v0
	v_mov_b32_e32 v75, v0
	v_mov_b32_e32 v76, v0
	v_mov_b32_e32 v77, v0
	v_mov_b32_e32 v78, v0
	v_mov_b32_e32 v79, v0
	v_mov_b32_e32 v88, v0
	v_mov_b32_e32 v89, v0
	v_mov_b32_e32 v90, v0
	v_mov_b32_e32 v91, v0
	v_mov_b32_e32 v92, v0
	v_mov_b32_e32 v93, v0
	v_mov_b32_e32 v94, v0
	v_mov_b32_e32 v95, v0
	v_mov_b32_e32 v104, v0
	v_mov_b32_e32 v105, v0
	v_mov_b32_e32 v106, v0
	v_mov_b32_e32 v107, v0
	v_mov_b32_e32 v108, v0
	v_mov_b32_e32 v109, v0
	v_mov_b32_e32 v110, v0
	v_mov_b32_e32 v111, v0
	v_mov_b32_e32 v120, v0
	v_mov_b32_e32 v121, v0
	v_mov_b32_e32 v122, v0
	v_mov_b32_e32 v123, v0
	v_mov_b32_e32 v124, v0
	v_mov_b32_e32 v125, v0
	v_mov_b32_e32 v126, v0
	v_mov_b32_e32 v127, v0
	.p2align	6

.LBB0_376:
	s_ashr_i32 s23, s22, 31
	s_lshl_b64 s[26:27], s[22:23], 17
	s_add_u32 s26, s30, s26
	s_addc_u32 s27, s31, s27
	s_andn2_b64 vcc, exec, s[18:19]
	s_mov_b32 s44, 0
	s_cbranch_vccnz .LBB0_380
	s_and_b64 s[4:5], s[4:5], exec
	s_cselect_b32 s23, s27, s7
	s_cselect_b32 s29, s26, s6
	s_add_u32 s4, s6, 0x10080
	s_addc_u32 s5, s7, 0
	s_add_u32 s6, s0, 0x100
	v_mov_b32_e32 v0, 0
	s_addc_u32 s7, s1, 0
	v_mov_b32_e32 v1, v0
	v_mov_b32_e32 v2, v0
	v_mov_b32_e32 v3, v0
	v_mov_b32_e32 v4, v0
	v_mov_b32_e32 v5, v0
	v_mov_b32_e32 v6, v0
	v_mov_b32_e32 v7, v0
	v_mov_b32_e32 v16, v0
	v_mov_b32_e32 v17, v0
	v_mov_b32_e32 v18, v0
	v_mov_b32_e32 v19, v0
	v_mov_b32_e32 v20, v0
	v_mov_b32_e32 v21, v0
	v_mov_b32_e32 v22, v0
	v_mov_b32_e32 v23, v0
	v_mov_b32_e32 v32, v0
	v_mov_b32_e32 v33, v0
	v_mov_b32_e32 v34, v0
	v_mov_b32_e32 v35, v0
	v_mov_b32_e32 v36, v0
	v_mov_b32_e32 v37, v0
	v_mov_b32_e32 v38, v0
	v_mov_b32_e32 v39, v0
	v_mov_b32_e32 v48, v0
	v_mov_b32_e32 v49, v0
	v_mov_b32_e32 v50, v0
	v_mov_b32_e32 v51, v0
	v_mov_b32_e32 v52, v0
	v_mov_b32_e32 v53, v0
	v_mov_b32_e32 v54, v0
	v_mov_b32_e32 v55, v0
	v_mov_b32_e32 v8, v0
	v_mov_b32_e32 v9, v0
	v_mov_b32_e32 v10, v0
	v_mov_b32_e32 v11, v0
	v_mov_b32_e32 v12, v0
	v_mov_b32_e32 v13, v0
	v_mov_b32_e32 v14, v0
	v_mov_b32_e32 v15, v0
	v_mov_b32_e32 v24, v0
	v_mov_b32_e32 v25, v0
	v_mov_b32_e32 v26, v0
	v_mov_b32_e32 v27, v0
	v_mov_b32_e32 v28, v0
	v_mov_b32_e32 v29, v0
	v_mov_b32_e32 v30, v0
	v_mov_b32_e32 v31, v0
	v_mov_b32_e32 v40, v0
	v_mov_b32_e32 v41, v0
	v_mov_b32_e32 v42, v0
	v_mov_b32_e32 v43, v0
	v_mov_b32_e32 v44, v0
	v_mov_b32_e32 v45, v0
	v_mov_b32_e32 v46, v0
	v_mov_b32_e32 v47, v0
	v_mov_b32_e32 v56, v0
	v_mov_b32_e32 v57, v0
	v_mov_b32_e32 v58, v0
	v_mov_b32_e32 v59, v0
	v_mov_b32_e32 v60, v0
	v_mov_b32_e32 v61, v0
	v_mov_b32_e32 v62, v0
	v_mov_b32_e32 v63, v0
	v_mov_b32_e32 v64, v0
	v_mov_b32_e32 v65, v0
	v_mov_b32_e32 v66, v0
	v_mov_b32_e32 v67, v0
	v_mov_b32_e32 v68, v0
	v_mov_b32_e32 v69, v0
	v_mov_b32_e32 v70, v0
	v_mov_b32_e32 v71, v0
	v_mov_b32_e32 v96, v0
	v_mov_b32_e32 v97, v0
	v_mov_b32_e32 v98, v0
	v_mov_b32_e32 v99, v0
	v_mov_b32_e32 v100, v0
	v_mov_b32_e32 v101, v0
	v_mov_b32_e32 v102, v0
	v_mov_b32_e32 v103, v0
	v_mov_b32_e32 v112, v0
	v_mov_b32_e32 v113, v0
	v_mov_b32_e32 v114, v0
	v_mov_b32_e32 v115, v0
	v_mov_b32_e32 v116, v0
	v_mov_b32_e32 v117, v0
	v_mov_b32_e32 v118, v0
	v_mov_b32_e32 v119, v0
	v_mov_b32_e32 v128, v0
	v_mov_b32_e32 v129, v0
	v_mov_b32_e32 v130, v0
	v_mov_b32_e32 v131, v0
	v_mov_b32_e32 v132, v0
	v_mov_b32_e32 v133, v0
	v_mov_b32_e32 v134, v0
	v_mov_b32_e32 v135, v0
	v_mov_b32_e32 v84, v0
	v_mov_b32_e32 v85, v0
	v_mov_b32_e32 v86, v0
	v_mov_b32_e32 v87, v0
	v_mov_b32_e32 v88, v0
	v_mov_b32_e32 v89, v0
	v_mov_b32_e32 v90, v0
	v_mov_b32_e32 v91, v0
	v_mov_b32_e32 v104, v0
	v_mov_b32_e32 v105, v0
	v_mov_b32_e32 v106, v0
	v_mov_b32_e32 v107, v0
	v_mov_b32_e32 v108, v0
	v_mov_b32_e32 v109, v0
	v_mov_b32_e32 v110, v0
	v_mov_b32_e32 v111, v0
	v_mov_b32_e32 v120, v0
	v_mov_b32_e32 v121, v0
	v_mov_b32_e32 v122, v0
	v_mov_b32_e32 v123, v0
	v_mov_b32_e32 v124, v0
	v_mov_b32_e32 v125, v0
	v_mov_b32_e32 v126, v0
	v_mov_b32_e32 v127, v0
	v_mov_b32_e32 v136, v0
	v_mov_b32_e32 v137, v0
	v_mov_b32_e32 v138, v0
	v_mov_b32_e32 v139, v0
	v_mov_b32_e32 v140, v0
	v_mov_b32_e32 v141, v0
	v_mov_b32_e32 v142, v0
	v_mov_b32_e32 v143, v0
	.p2align	6

.LBB0_865:
	s_ashr_i32 s45, s44, 31
	s_lshl_b64 s[0:1], s[44:45], 19
	s_add_u32 s22, s42, s0
	s_addc_u32 s23, s46, s1
	s_ashr_i32 s0, s44, 5
	s_ashr_i32 s1, s0, 31
	s_lshl_b64 s[0:1], s[0:1], 11
	s_add_u32 s88, s22, s0
	v_mov_b32_e32 v95, 0
	s_addc_u32 s89, s23, s1
	s_andn2_b64 vcc, exec, s[26:27]
	v_mov_b32_e32 v94, v95
	v_mov_b32_e32 v93, v95
	v_mov_b32_e32 v92, v95
	v_mov_b32_e32 v91, v95
	v_mov_b32_e32 v90, v95
	v_mov_b32_e32 v89, v95
	v_mov_b32_e32 v88, v95
	v_mov_b32_e32 v83, v95
	v_mov_b32_e32 v82, v95
	v_mov_b32_e32 v81, v95
	v_mov_b32_e32 v80, v95
	v_mov_b32_e32 v79, v95
	v_mov_b32_e32 v78, v95
	v_mov_b32_e32 v77, v95
	v_mov_b32_e32 v76, v95
	v_mov_b32_e32 v71, v95
	v_mov_b32_e32 v70, v95
	v_mov_b32_e32 v69, v95
	v_mov_b32_e32 v68, v95
	v_mov_b32_e32 v67, v95
	v_mov_b32_e32 v66, v95
	v_mov_b32_e32 v65, v95
	v_mov_b32_e32 v64, v95
	v_mov_b32_e32 v59, v95
	v_mov_b32_e32 v58, v95
	v_mov_b32_e32 v57, v95
	v_mov_b32_e32 v56, v95
	v_mov_b32_e32 v55, v95
	v_mov_b32_e32 v54, v95
	v_mov_b32_e32 v53, v95
	v_mov_b32_e32 v52, v95
	v_mov_b32_e32 v87, v95
	v_mov_b32_e32 v86, v95
	v_mov_b32_e32 v85, v95
	v_mov_b32_e32 v84, v95
	v_mov_b32_e32 v127, v95
	v_mov_b32_e32 v126, v95
	v_mov_b32_e32 v125, v95
	v_mov_b32_e32 v124, v95
	v_mov_b32_e32 v75, v95
	v_mov_b32_e32 v74, v95
	v_mov_b32_e32 v73, v95
	v_mov_b32_e32 v72, v95
	v_mov_b32_e32 v123, v95
	v_mov_b32_e32 v122, v95
	v_mov_b32_e32 v121, v95
	v_mov_b32_e32 v120, v95
	v_mov_b32_e32 v63, v95
	v_mov_b32_e32 v62, v95
	v_mov_b32_e32 v61, v95
	v_mov_b32_e32 v60, v95
	v_mov_b32_e32 v119, v95
	v_mov_b32_e32 v118, v95
	v_mov_b32_e32 v117, v95
	v_mov_b32_e32 v116, v95
	v_mov_b32_e32 v51, v95
	v_mov_b32_e32 v50, v95
	v_mov_b32_e32 v49, v95
	v_mov_b32_e32 v48, v95
	v_mov_b32_e32 v115, v95
	v_mov_b32_e32 v114, v95
	v_mov_b32_e32 v113, v95
	v_mov_b32_e32 v112, v95
	v_mov_b32_e32 v47, v95
	v_mov_b32_e32 v46, v95
	v_mov_b32_e32 v45, v95
	v_mov_b32_e32 v44, v95
	v_mov_b32_e32 v43, v95
	v_mov_b32_e32 v42, v95
	v_mov_b32_e32 v41, v95
	v_mov_b32_e32 v40, v95
	v_mov_b32_e32 v35, v95
	v_mov_b32_e32 v34, v95
	v_mov_b32_e32 v33, v95
	v_mov_b32_e32 v32, v95
	v_mov_b32_e32 v31, v95
	v_mov_b32_e32 v30, v95
	v_mov_b32_e32 v29, v95
	v_mov_b32_e32 v28, v95
	v_mov_b32_e32 v23, v95
	v_mov_b32_e32 v22, v95
	v_mov_b32_e32 v21, v95
	v_mov_b32_e32 v20, v95
	v_mov_b32_e32 v19, v95
	v_mov_b32_e32 v18, v95
	v_mov_b32_e32 v17, v95
	v_mov_b32_e32 v16, v95
	v_mov_b32_e32 v11, v95
	v_mov_b32_e32 v10, v95
	v_mov_b32_e32 v9, v95
	v_mov_b32_e32 v8, v95
	v_mov_b32_e32 v7, v95
	v_mov_b32_e32 v6, v95
	v_mov_b32_e32 v5, v95
	v_mov_b32_e32 v4, v95
	v_mov_b32_e32 v39, v95
	v_mov_b32_e32 v38, v95
	v_mov_b32_e32 v37, v95
	v_mov_b32_e32 v36, v95
	v_mov_b32_e32 v111, v95
	v_mov_b32_e32 v110, v95
	v_mov_b32_e32 v109, v95
	v_mov_b32_e32 v108, v95
	v_mov_b32_e32 v27, v95
	v_mov_b32_e32 v26, v95
	v_mov_b32_e32 v25, v95
	v_mov_b32_e32 v24, v95
	v_mov_b32_e32 v107, v95
	v_mov_b32_e32 v106, v95
	v_mov_b32_e32 v105, v95
	v_mov_b32_e32 v104, v95
	v_mov_b32_e32 v15, v95
	v_mov_b32_e32 v14, v95
	v_mov_b32_e32 v13, v95
	v_mov_b32_e32 v12, v95
	v_mov_b32_e32 v103, v95
	v_mov_b32_e32 v102, v95
	v_mov_b32_e32 v101, v95
	v_mov_b32_e32 v100, v95
	v_mov_b32_e32 v3, v95
	v_mov_b32_e32 v2, v95
	v_mov_b32_e32 v1, v95
	v_mov_b32_e32 v0, v95
	v_mov_b32_e32 v99, v95
	v_mov_b32_e32 v98, v95
	v_mov_b32_e32 v97, v95
	v_mov_b32_e32 v96, v95
	s_cbranch_vccnz .LBB0_888
	s_and_b64 s[0:1], s[4:5], exec
	s_cselect_b32 s22, s89, s21
	s_cselect_b32 s23, s88, s20
	s_add_u32 s4, s20, 0x40080
	s_addc_u32 s5, s21, 0
	s_add_u32 s6, s6, 0x100
	v_mov_b32_e32 v96, 0
	v_mov_b32_e32 v178, 0x400
	s_addc_u32 s7, s7, 0
	s_mov_b32 s0, 0
	v_mov_b32_e32 v97, v96
	v_mov_b32_e32 v98, v96
	v_mov_b32_e32 v99, v96
	v_mov_b32_e32 v0, v96
	v_mov_b32_e32 v1, v96
	v_mov_b32_e32 v2, v96
	v_mov_b32_e32 v3, v96
	v_mov_b32_e32 v100, v96
	v_mov_b32_e32 v101, v96
	v_mov_b32_e32 v102, v96
	v_mov_b32_e32 v103, v96
	v_mov_b32_e32 v12, v96
	v_mov_b32_e32 v13, v96
	v_mov_b32_e32 v14, v96
	v_mov_b32_e32 v15, v96
	v_mov_b32_e32 v104, v96
	v_mov_b32_e32 v105, v96
	v_mov_b32_e32 v106, v96
	v_mov_b32_e32 v107, v96
	v_mov_b32_e32 v24, v96
	v_mov_b32_e32 v25, v96
	v_mov_b32_e32 v26, v96
	v_mov_b32_e32 v27, v96
	v_mov_b32_e32 v108, v96
	v_mov_b32_e32 v109, v96
	v_mov_b32_e32 v110, v96
	v_mov_b32_e32 v111, v96
	v_mov_b32_e32 v36, v96
	v_mov_b32_e32 v37, v96
	v_mov_b32_e32 v38, v96
	v_mov_b32_e32 v39, v96
	v_mov_b32_e32 v4, v96
	v_mov_b32_e32 v5, v96
	v_mov_b32_e32 v6, v96
	v_mov_b32_e32 v7, v96
	v_mov_b32_e32 v8, v96
	v_mov_b32_e32 v9, v96
	v_mov_b32_e32 v10, v96
	v_mov_b32_e32 v11, v96
	v_mov_b32_e32 v16, v96
	v_mov_b32_e32 v17, v96
	v_mov_b32_e32 v18, v96
	v_mov_b32_e32 v19, v96
	v_mov_b32_e32 v20, v96
	v_mov_b32_e32 v21, v96
	v_mov_b32_e32 v22, v96
	v_mov_b32_e32 v23, v96
	v_mov_b32_e32 v28, v96
	v_mov_b32_e32 v29, v96
	v_mov_b32_e32 v30, v96
	v_mov_b32_e32 v31, v96
	v_mov_b32_e32 v32, v96
	v_mov_b32_e32 v33, v96
	v_mov_b32_e32 v34, v96
	v_mov_b32_e32 v35, v96
	v_mov_b32_e32 v40, v96
	v_mov_b32_e32 v41, v96
	v_mov_b32_e32 v42, v96
	v_mov_b32_e32 v43, v96
	v_mov_b32_e32 v44, v96
	v_mov_b32_e32 v45, v96
	v_mov_b32_e32 v46, v96
	v_mov_b32_e32 v47, v96
	v_mov_b32_e32 v112, v96
	v_mov_b32_e32 v113, v96
	v_mov_b32_e32 v114, v96
	v_mov_b32_e32 v115, v96
	v_mov_b32_e32 v48, v96
	v_mov_b32_e32 v49, v96
	v_mov_b32_e32 v50, v96
	v_mov_b32_e32 v51, v96
	v_mov_b32_e32 v116, v96
	v_mov_b32_e32 v117, v96
	v_mov_b32_e32 v118, v96
	v_mov_b32_e32 v119, v96
	v_mov_b32_e32 v60, v96
	v_mov_b32_e32 v61, v96
	v_mov_b32_e32 v62, v96
	v_mov_b32_e32 v63, v96
	v_mov_b32_e32 v120, v96
	v_mov_b32_e32 v121, v96
	v_mov_b32_e32 v122, v96
	v_mov_b32_e32 v123, v96
	v_mov_b32_e32 v72, v96
	v_mov_b32_e32 v73, v96
	v_mov_b32_e32 v74, v96
	v_mov_b32_e32 v75, v96
	v_mov_b32_e32 v124, v96
	v_mov_b32_e32 v125, v96
	v_mov_b32_e32 v126, v96
	v_mov_b32_e32 v127, v96
	v_mov_b32_e32 v84, v96
	v_mov_b32_e32 v85, v96
	v_mov_b32_e32 v86, v96
	v_mov_b32_e32 v87, v96
	v_mov_b32_e32 v52, v96
	v_mov_b32_e32 v53, v96
	v_mov_b32_e32 v54, v96
	v_mov_b32_e32 v55, v96
	v_mov_b32_e32 v56, v96
	v_mov_b32_e32 v57, v96
	v_mov_b32_e32 v58, v96
	v_mov_b32_e32 v59, v96
	v_mov_b32_e32 v64, v96
	v_mov_b32_e32 v65, v96
	v_mov_b32_e32 v66, v96
	v_mov_b32_e32 v67, v96
	v_mov_b32_e32 v68, v96
	v_mov_b32_e32 v69, v96
	v_mov_b32_e32 v70, v96
	v_mov_b32_e32 v71, v96
	v_mov_b32_e32 v76, v96
	v_mov_b32_e32 v77, v96
	v_mov_b32_e32 v78, v96
	v_mov_b32_e32 v79, v96
	v_mov_b32_e32 v80, v96
	v_mov_b32_e32 v81, v96
	v_mov_b32_e32 v82, v96
	v_mov_b32_e32 v83, v96
	v_mov_b32_e32 v88, v96
	v_mov_b32_e32 v89, v96
	v_mov_b32_e32 v90, v96
	v_mov_b32_e32 v91, v96
	v_mov_b32_e32 v92, v96
	v_mov_b32_e32 v93, v96
	v_mov_b32_e32 v94, v96
	v_mov_b32_e32 v95, v96
	.p2align	6

.LBB0_1044:
	s_ashr_i32 s13, s12, 31
	s_lshl_b64 s[14:15], s[12:13], 19
	s_add_u32 s13, s24, s14
	s_addc_u32 s15, s25, s15
	s_ashr_i32 s11, s10, 31
	s_lshl_b64 s[16:17], s[10:11], 9
	s_add_u32 s14, s13, s16
	s_addc_u32 s15, s15, s17
	s_add_u32 s16, s26, s16
	v_mov_b32_e32 v127, 0
	s_addc_u32 s17, s27, s17
	s_andn2_b64 vcc, exec, s[6:7]
	v_mov_b32_e32 v126, v127
	v_mov_b32_e32 v125, v127
	v_mov_b32_e32 v124, v127
	v_mov_b32_e32 v123, v127
	v_mov_b32_e32 v122, v127
	v_mov_b32_e32 v121, v127
	v_mov_b32_e32 v120, v127
	v_mov_b32_e32 v111, v127
	v_mov_b32_e32 v110, v127
	v_mov_b32_e32 v109, v127
	v_mov_b32_e32 v108, v127
	v_mov_b32_e32 v107, v127
	v_mov_b32_e32 v106, v127
	v_mov_b32_e32 v105, v127
	v_mov_b32_e32 v104, v127
	v_mov_b32_e32 v95, v127
	v_mov_b32_e32 v94, v127
	v_mov_b32_e32 v93, v127
	v_mov_b32_e32 v92, v127
	v_mov_b32_e32 v91, v127
	v_mov_b32_e32 v90, v127
	v_mov_b32_e32 v89, v127
	v_mov_b32_e32 v88, v127
	v_mov_b32_e32 v79, v127
	v_mov_b32_e32 v78, v127
	v_mov_b32_e32 v77, v127
	v_mov_b32_e32 v76, v127
	v_mov_b32_e32 v75, v127
	v_mov_b32_e32 v74, v127
	v_mov_b32_e32 v73, v127
	v_mov_b32_e32 v72, v127
	v_mov_b32_e32 v119, v127
	v_mov_b32_e32 v118, v127
	v_mov_b32_e32 v117, v127
	v_mov_b32_e32 v116, v127
	v_mov_b32_e32 v115, v127
	v_mov_b32_e32 v114, v127
	v_mov_b32_e32 v113, v127
	v_mov_b32_e32 v112, v127
	v_mov_b32_e32 v103, v127
	v_mov_b32_e32 v102, v127
	v_mov_b32_e32 v101, v127
	v_mov_b32_e32 v100, v127
	v_mov_b32_e32 v99, v127
	v_mov_b32_e32 v98, v127
	v_mov_b32_e32 v97, v127
	v_mov_b32_e32 v96, v127
	v_mov_b32_e32 v87, v127
	v_mov_b32_e32 v86, v127
	v_mov_b32_e32 v85, v127
	v_mov_b32_e32 v84, v127
	v_mov_b32_e32 v83, v127
	v_mov_b32_e32 v82, v127
	v_mov_b32_e32 v81, v127
	v_mov_b32_e32 v80, v127
	v_mov_b32_e32 v71, v127
	v_mov_b32_e32 v70, v127
	v_mov_b32_e32 v69, v127
	v_mov_b32_e32 v68, v127
	v_mov_b32_e32 v67, v127
	v_mov_b32_e32 v66, v127
	v_mov_b32_e32 v65, v127
	v_mov_b32_e32 v64, v127
	v_mov_b32_e32 v63, v127
	v_mov_b32_e32 v62, v127
	v_mov_b32_e32 v61, v127
	v_mov_b32_e32 v60, v127
	v_mov_b32_e32 v59, v127
	v_mov_b32_e32 v58, v127
	v_mov_b32_e32 v57, v127
	v_mov_b32_e32 v56, v127
	v_mov_b32_e32 v47, v127
	v_mov_b32_e32 v46, v127
	v_mov_b32_e32 v45, v127
	v_mov_b32_e32 v44, v127
	v_mov_b32_e32 v43, v127
	v_mov_b32_e32 v42, v127
	v_mov_b32_e32 v41, v127
	v_mov_b32_e32 v40, v127
	v_mov_b32_e32 v31, v127
	v_mov_b32_e32 v30, v127
	v_mov_b32_e32 v29, v127
	v_mov_b32_e32 v28, v127
	v_mov_b32_e32 v27, v127
	v_mov_b32_e32 v26, v127
	v_mov_b32_e32 v25, v127
	v_mov_b32_e32 v24, v127
	v_mov_b32_e32 v15, v127
	v_mov_b32_e32 v14, v127
	v_mov_b32_e32 v13, v127
	v_mov_b32_e32 v12, v127
	v_mov_b32_e32 v11, v127
	v_mov_b32_e32 v10, v127
	v_mov_b32_e32 v9, v127
	v_mov_b32_e32 v8, v127
	v_mov_b32_e32 v55, v127
	v_mov_b32_e32 v54, v127
	v_mov_b32_e32 v53, v127
	v_mov_b32_e32 v52, v127
	v_mov_b32_e32 v51, v127
	v_mov_b32_e32 v50, v127
	v_mov_b32_e32 v49, v127
	v_mov_b32_e32 v48, v127
	v_mov_b32_e32 v39, v127
	v_mov_b32_e32 v38, v127
	v_mov_b32_e32 v37, v127
	v_mov_b32_e32 v36, v127
	v_mov_b32_e32 v35, v127
	v_mov_b32_e32 v34, v127
	v_mov_b32_e32 v33, v127
	v_mov_b32_e32 v32, v127
	v_mov_b32_e32 v23, v127
	v_mov_b32_e32 v22, v127
	v_mov_b32_e32 v21, v127
	v_mov_b32_e32 v20, v127
	v_mov_b32_e32 v19, v127
	v_mov_b32_e32 v18, v127
	v_mov_b32_e32 v17, v127
	v_mov_b32_e32 v16, v127
	v_mov_b32_e32 v7, v127
	v_mov_b32_e32 v6, v127
	v_mov_b32_e32 v5, v127
	v_mov_b32_e32 v4, v127
	v_mov_b32_e32 v3, v127
	v_mov_b32_e32 v2, v127
	v_mov_b32_e32 v1, v127
	v_mov_b32_e32 v0, v127
	s_cbranch_vccnz .LBB0_1047
	s_and_b64 s[22:23], s[2:3], exec
	s_cselect_b32 s11, s15, s21
	s_cselect_b32 s13, s14, s20
	s_cselect_b32 s19, s17, s1
	s_cselect_b32 s44, s16, s0
	s_add_u32 s20, s20, 0x40080
	s_addc_u32 s21, s21, 0
	s_add_u32 s45, s0, 0x100
	v_mov_b32_e32 v0, 0
	s_addc_u32 s46, s1, 0
	s_mov_b32 s0, 0
	v_mov_b32_e32 v1, v0
	v_mov_b32_e32 v2, v0
	v_mov_b32_e32 v3, v0
	v_mov_b32_e32 v4, v0
	v_mov_b32_e32 v5, v0
	v_mov_b32_e32 v6, v0
	v_mov_b32_e32 v7, v0
	v_mov_b32_e32 v16, v0
	v_mov_b32_e32 v17, v0
	v_mov_b32_e32 v18, v0
	v_mov_b32_e32 v19, v0
	v_mov_b32_e32 v20, v0
	v_mov_b32_e32 v21, v0
	v_mov_b32_e32 v22, v0
	v_mov_b32_e32 v23, v0
	v_mov_b32_e32 v32, v0
	v_mov_b32_e32 v33, v0
	v_mov_b32_e32 v34, v0
	v_mov_b32_e32 v35, v0
	v_mov_b32_e32 v36, v0
	v_mov_b32_e32 v37, v0
	v_mov_b32_e32 v38, v0
	v_mov_b32_e32 v39, v0
	v_mov_b32_e32 v48, v0
	v_mov_b32_e32 v49, v0
	v_mov_b32_e32 v50, v0
	v_mov_b32_e32 v51, v0
	v_mov_b32_e32 v52, v0
	v_mov_b32_e32 v53, v0
	v_mov_b32_e32 v54, v0
	v_mov_b32_e32 v55, v0
	v_mov_b32_e32 v8, v0
	v_mov_b32_e32 v9, v0
	v_mov_b32_e32 v10, v0
	v_mov_b32_e32 v11, v0
	v_mov_b32_e32 v12, v0
	v_mov_b32_e32 v13, v0
	v_mov_b32_e32 v14, v0
	v_mov_b32_e32 v15, v0
	v_mov_b32_e32 v24, v0
	v_mov_b32_e32 v25, v0
	v_mov_b32_e32 v26, v0
	v_mov_b32_e32 v27, v0
	v_mov_b32_e32 v28, v0
	v_mov_b32_e32 v29, v0
	v_mov_b32_e32 v30, v0
	v_mov_b32_e32 v31, v0
	v_mov_b32_e32 v40, v0
	v_mov_b32_e32 v41, v0
	v_mov_b32_e32 v42, v0
	v_mov_b32_e32 v43, v0
	v_mov_b32_e32 v44, v0
	v_mov_b32_e32 v45, v0
	v_mov_b32_e32 v46, v0
	v_mov_b32_e32 v47, v0
	v_mov_b32_e32 v56, v0
	v_mov_b32_e32 v57, v0
	v_mov_b32_e32 v58, v0
	v_mov_b32_e32 v59, v0
	v_mov_b32_e32 v60, v0
	v_mov_b32_e32 v61, v0
	v_mov_b32_e32 v62, v0
	v_mov_b32_e32 v63, v0
	v_mov_b32_e32 v64, v0
	v_mov_b32_e32 v65, v0
	v_mov_b32_e32 v66, v0
	v_mov_b32_e32 v67, v0
	v_mov_b32_e32 v68, v0
	v_mov_b32_e32 v69, v0
	v_mov_b32_e32 v70, v0
	v_mov_b32_e32 v71, v0
	v_mov_b32_e32 v80, v0
	v_mov_b32_e32 v81, v0
	v_mov_b32_e32 v82, v0
	v_mov_b32_e32 v83, v0
	v_mov_b32_e32 v84, v0
	v_mov_b32_e32 v85, v0
	v_mov_b32_e32 v86, v0
	v_mov_b32_e32 v87, v0
	v_mov_b32_e32 v96, v0
	v_mov_b32_e32 v97, v0
	v_mov_b32_e32 v98, v0
	v_mov_b32_e32 v99, v0
	v_mov_b32_e32 v100, v0
	v_mov_b32_e32 v101, v0
	v_mov_b32_e32 v102, v0
	v_mov_b32_e32 v103, v0
	v_mov_b32_e32 v112, v0
	v_mov_b32_e32 v113, v0
	v_mov_b32_e32 v114, v0
	v_mov_b32_e32 v115, v0
	v_mov_b32_e32 v116, v0
	v_mov_b32_e32 v117, v0
	v_mov_b32_e32 v118, v0
	v_mov_b32_e32 v119, v0
	v_mov_b32_e32 v72, v0
	v_mov_b32_e32 v73, v0
	v_mov_b32_e32 v74, v0
	v_mov_b32_e32 v75, v0
	v_mov_b32_e32 v76, v0
	v_mov_b32_e32 v77, v0
	v_mov_b32_e32 v78, v0
	v_mov_b32_e32 v79, v0
	v_mov_b32_e32 v88, v0
	v_mov_b32_e32 v89, v0
	v_mov_b32_e32 v90, v0
	v_mov_b32_e32 v91, v0
	v_mov_b32_e32 v92, v0
	v_mov_b32_e32 v93, v0
	v_mov_b32_e32 v94, v0
	v_mov_b32_e32 v95, v0
	v_mov_b32_e32 v104, v0
	v_mov_b32_e32 v105, v0
	v_mov_b32_e32 v106, v0
	v_mov_b32_e32 v107, v0
	v_mov_b32_e32 v108, v0
	v_mov_b32_e32 v109, v0
	v_mov_b32_e32 v110, v0
	v_mov_b32_e32 v111, v0
	v_mov_b32_e32 v120, v0
	v_mov_b32_e32 v121, v0
	v_mov_b32_e32 v122, v0
	v_mov_b32_e32 v123, v0
	v_mov_b32_e32 v124, v0
	v_mov_b32_e32 v125, v0
	v_mov_b32_e32 v126, v0
	v_mov_b32_e32 v127, v0
	.p2align	6

.LBB0_1395:
	v_mov_b32_e32 v139, 0
	s_andn2_b64 vcc, exec, s[28:29]
	v_mov_b32_e32 v138, v139
	v_mov_b32_e32 v137, v139
	v_mov_b32_e32 v136, v139
	v_mov_b32_e32 v143, v139
	v_mov_b32_e32 v142, v139
	v_mov_b32_e32 v141, v139
	v_mov_b32_e32 v140, v139
	v_mov_b32_e32 v127, v139
	v_mov_b32_e32 v126, v139
	v_mov_b32_e32 v125, v139
	v_mov_b32_e32 v124, v139
	v_mov_b32_e32 v123, v139
	v_mov_b32_e32 v122, v139
	v_mov_b32_e32 v121, v139
	v_mov_b32_e32 v120, v139
	v_mov_b32_e32 v95, v139
	v_mov_b32_e32 v94, v139
	v_mov_b32_e32 v93, v139
	v_mov_b32_e32 v92, v139
	v_mov_b32_e32 v91, v139
	v_mov_b32_e32 v90, v139
	v_mov_b32_e32 v89, v139
	v_mov_b32_e32 v88, v139
	v_mov_b32_e32 v79, v139
	v_mov_b32_e32 v78, v139
	v_mov_b32_e32 v77, v139
	v_mov_b32_e32 v76, v139
	v_mov_b32_e32 v75, v139
	v_mov_b32_e32 v74, v139
	v_mov_b32_e32 v73, v139
	v_mov_b32_e32 v72, v139
	v_mov_b32_e32 v135, v139
	v_mov_b32_e32 v134, v139
	v_mov_b32_e32 v133, v139
	v_mov_b32_e32 v132, v139
	v_mov_b32_e32 v131, v139
	v_mov_b32_e32 v130, v139
	v_mov_b32_e32 v129, v139
	v_mov_b32_e32 v128, v139
	v_mov_b32_e32 v119, v139
	v_mov_b32_e32 v118, v139
	v_mov_b32_e32 v117, v139
	v_mov_b32_e32 v116, v139
	v_mov_b32_e32 v115, v139
	v_mov_b32_e32 v114, v139
	v_mov_b32_e32 v113, v139
	v_mov_b32_e32 v112, v139
	v_mov_b32_e32 v87, v139
	v_mov_b32_e32 v86, v139
	v_mov_b32_e32 v85, v139
	v_mov_b32_e32 v84, v139
	v_mov_b32_e32 v83, v139
	v_mov_b32_e32 v82, v139
	v_mov_b32_e32 v81, v139
	v_mov_b32_e32 v80, v139
	v_mov_b32_e32 v71, v139
	v_mov_b32_e32 v70, v139
	v_mov_b32_e32 v69, v139
	v_mov_b32_e32 v68, v139
	v_mov_b32_e32 v67, v139
	v_mov_b32_e32 v66, v139
	v_mov_b32_e32 v65, v139
	v_mov_b32_e32 v64, v139
	v_mov_b32_e32 v63, v139
	v_mov_b32_e32 v62, v139
	v_mov_b32_e32 v61, v139
	v_mov_b32_e32 v60, v139
	v_mov_b32_e32 v59, v139
	v_mov_b32_e32 v58, v139
	v_mov_b32_e32 v57, v139
	v_mov_b32_e32 v56, v139
	v_mov_b32_e32 v47, v139
	v_mov_b32_e32 v46, v139
	v_mov_b32_e32 v45, v139
	v_mov_b32_e32 v44, v139
	v_mov_b32_e32 v43, v139
	v_mov_b32_e32 v42, v139
	v_mov_b32_e32 v41, v139
	v_mov_b32_e32 v40, v139
	v_mov_b32_e32 v31, v139
	v_mov_b32_e32 v30, v139
	v_mov_b32_e32 v29, v139
	v_mov_b32_e32 v28, v139
	v_mov_b32_e32 v27, v139
	v_mov_b32_e32 v26, v139
	v_mov_b32_e32 v25, v139
	v_mov_b32_e32 v24, v139
	v_mov_b32_e32 v15, v139
	v_mov_b32_e32 v14, v139
	v_mov_b32_e32 v13, v139
	v_mov_b32_e32 v12, v139
	v_mov_b32_e32 v11, v139
	v_mov_b32_e32 v10, v139
	v_mov_b32_e32 v9, v139
	v_mov_b32_e32 v8, v139
	v_mov_b32_e32 v55, v139
	v_mov_b32_e32 v54, v139
	v_mov_b32_e32 v53, v139
	v_mov_b32_e32 v52, v139
	v_mov_b32_e32 v51, v139
	v_mov_b32_e32 v50, v139
	v_mov_b32_e32 v49, v139
	v_mov_b32_e32 v48, v139
	v_mov_b32_e32 v39, v139
	v_mov_b32_e32 v38, v139
	v_mov_b32_e32 v37, v139
	v_mov_b32_e32 v36, v139
	v_mov_b32_e32 v35, v139
	v_mov_b32_e32 v34, v139
	v_mov_b32_e32 v33, v139
	v_mov_b32_e32 v32, v139
	v_mov_b32_e32 v23, v139
	v_mov_b32_e32 v22, v139
	v_mov_b32_e32 v21, v139
	v_mov_b32_e32 v20, v139
	v_mov_b32_e32 v19, v139
	v_mov_b32_e32 v18, v139
	v_mov_b32_e32 v17, v139
	v_mov_b32_e32 v16, v139
	v_mov_b32_e32 v7, v139
	v_mov_b32_e32 v6, v139
	v_mov_b32_e32 v5, v139
	v_mov_b32_e32 v4, v139
	v_mov_b32_e32 v3, v139
	v_mov_b32_e32 v2, v139
	v_mov_b32_e32 v1, v139
	v_mov_b32_e32 v0, v139
	s_cbranch_vccnz .LBB0_1399
	s_add_u32 s6, s88, 0x40080
	s_addc_u32 s7, s89, 0
	s_add_u32 s65, s66, 0x100
	v_mov_b32_e32 v0, 0
	s_addc_u32 s87, s67, 0
	s_mov_b32 s66, 0
	v_mov_b32_e32 v1, v0
	v_mov_b32_e32 v2, v0
	v_mov_b32_e32 v3, v0
	v_mov_b32_e32 v4, v0
	v_mov_b32_e32 v5, v0
	v_mov_b32_e32 v6, v0
	v_mov_b32_e32 v7, v0
	v_mov_b32_e32 v16, v0
	v_mov_b32_e32 v17, v0
	v_mov_b32_e32 v18, v0
	v_mov_b32_e32 v19, v0
	v_mov_b32_e32 v20, v0
	v_mov_b32_e32 v21, v0
	v_mov_b32_e32 v22, v0
	v_mov_b32_e32 v23, v0
	v_mov_b32_e32 v32, v0
	v_mov_b32_e32 v33, v0
	v_mov_b32_e32 v34, v0
	v_mov_b32_e32 v35, v0
	v_mov_b32_e32 v36, v0
	v_mov_b32_e32 v37, v0
	v_mov_b32_e32 v38, v0
	v_mov_b32_e32 v39, v0
	v_mov_b32_e32 v48, v0
	v_mov_b32_e32 v49, v0
	v_mov_b32_e32 v50, v0
	v_mov_b32_e32 v51, v0
	v_mov_b32_e32 v52, v0
	v_mov_b32_e32 v53, v0
	v_mov_b32_e32 v54, v0
	v_mov_b32_e32 v55, v0
	v_mov_b32_e32 v8, v0
	v_mov_b32_e32 v9, v0
	v_mov_b32_e32 v10, v0
	v_mov_b32_e32 v11, v0
	v_mov_b32_e32 v12, v0
	v_mov_b32_e32 v13, v0
	v_mov_b32_e32 v14, v0
	v_mov_b32_e32 v15, v0
	v_mov_b32_e32 v24, v0
	v_mov_b32_e32 v25, v0
	v_mov_b32_e32 v26, v0
	v_mov_b32_e32 v27, v0
	v_mov_b32_e32 v28, v0
	v_mov_b32_e32 v29, v0
	v_mov_b32_e32 v30, v0
	v_mov_b32_e32 v31, v0
	v_mov_b32_e32 v40, v0
	v_mov_b32_e32 v41, v0
	v_mov_b32_e32 v42, v0
	v_mov_b32_e32 v43, v0
	v_mov_b32_e32 v44, v0
	v_mov_b32_e32 v45, v0
	v_mov_b32_e32 v46, v0
	v_mov_b32_e32 v47, v0
	v_mov_b32_e32 v56, v0
	v_mov_b32_e32 v57, v0
	v_mov_b32_e32 v58, v0
	v_mov_b32_e32 v59, v0
	v_mov_b32_e32 v60, v0
	v_mov_b32_e32 v61, v0
	v_mov_b32_e32 v62, v0
	v_mov_b32_e32 v63, v0
	v_mov_b32_e32 v64, v0
	v_mov_b32_e32 v65, v0
	v_mov_b32_e32 v66, v0
	v_mov_b32_e32 v67, v0
	v_mov_b32_e32 v68, v0
	v_mov_b32_e32 v69, v0
	v_mov_b32_e32 v70, v0
	v_mov_b32_e32 v71, v0
	v_mov_b32_e32 v80, v0
	v_mov_b32_e32 v81, v0
	v_mov_b32_e32 v82, v0
	v_mov_b32_e32 v83, v0
	v_mov_b32_e32 v84, v0
	v_mov_b32_e32 v85, v0
	v_mov_b32_e32 v86, v0
	v_mov_b32_e32 v87, v0
	v_mov_b32_e32 v112, v0
	v_mov_b32_e32 v113, v0
	v_mov_b32_e32 v114, v0
	v_mov_b32_e32 v115, v0
	v_mov_b32_e32 v116, v0
	v_mov_b32_e32 v117, v0
	v_mov_b32_e32 v118, v0
	v_mov_b32_e32 v119, v0
	v_mov_b32_e32 v128, v0
	v_mov_b32_e32 v129, v0
	v_mov_b32_e32 v130, v0
	v_mov_b32_e32 v131, v0
	v_mov_b32_e32 v132, v0
	v_mov_b32_e32 v133, v0
	v_mov_b32_e32 v134, v0
	v_mov_b32_e32 v135, v0
	v_mov_b32_e32 v72, v0
	v_mov_b32_e32 v73, v0
	v_mov_b32_e32 v74, v0
	v_mov_b32_e32 v75, v0
	v_mov_b32_e32 v76, v0
	v_mov_b32_e32 v77, v0
	v_mov_b32_e32 v78, v0
	v_mov_b32_e32 v79, v0
	v_mov_b32_e32 v88, v0
	v_mov_b32_e32 v89, v0
	v_mov_b32_e32 v90, v0
	v_mov_b32_e32 v91, v0
	v_mov_b32_e32 v92, v0
	v_mov_b32_e32 v93, v0
	v_mov_b32_e32 v94, v0
	v_mov_b32_e32 v95, v0
	v_mov_b32_e32 v120, v0
	v_mov_b32_e32 v121, v0
	v_mov_b32_e32 v122, v0
	v_mov_b32_e32 v123, v0
	v_mov_b32_e32 v124, v0
	v_mov_b32_e32 v125, v0
	v_mov_b32_e32 v126, v0
	v_mov_b32_e32 v127, v0
	v_mov_b32_e32 v140, v0
	v_mov_b32_e32 v141, v0
	v_mov_b32_e32 v142, v0
	v_mov_b32_e32 v143, v0
	v_mov_b32_e32 v136, v0
	v_mov_b32_e32 v137, v0
	v_mov_b32_e32 v138, v0
	v_mov_b32_e32 v139, v0
	.p2align	6

.LBB0_1536:
	s_ashr_i32 s19, s18, 31
	s_lshl_b64 s[22:23], s[18:19], 19
	s_add_u32 s0, s26, s22
	s_addc_u32 s1, s27, s23
	s_ashr_i32 s22, s18, 5
	s_ashr_i32 s23, s22, 31
	s_lshl_b64 s[22:23], s[22:23], 11
	s_add_u32 s22, s0, s22
	v_mov_b32_e32 v123, 0
	s_addc_u32 s23, s1, s23
	s_andn2_b64 vcc, exec, s[14:15]
	v_mov_b32_e32 v122, v123
	v_mov_b32_e32 v121, v123
	v_mov_b32_e32 v120, v123
	v_mov_b32_e32 v127, v123
	v_mov_b32_e32 v126, v123
	v_mov_b32_e32 v125, v123
	v_mov_b32_e32 v124, v123
	v_mov_b32_e32 v111, v123
	v_mov_b32_e32 v110, v123
	v_mov_b32_e32 v109, v123
	v_mov_b32_e32 v108, v123
	v_mov_b32_e32 v107, v123
	v_mov_b32_e32 v106, v123
	v_mov_b32_e32 v105, v123
	v_mov_b32_e32 v104, v123
	v_mov_b32_e32 v95, v123
	v_mov_b32_e32 v94, v123
	v_mov_b32_e32 v93, v123
	v_mov_b32_e32 v92, v123
	v_mov_b32_e32 v91, v123
	v_mov_b32_e32 v90, v123
	v_mov_b32_e32 v89, v123
	v_mov_b32_e32 v88, v123
	v_mov_b32_e32 v79, v123
	v_mov_b32_e32 v78, v123
	v_mov_b32_e32 v77, v123
	v_mov_b32_e32 v76, v123
	v_mov_b32_e32 v75, v123
	v_mov_b32_e32 v74, v123
	v_mov_b32_e32 v73, v123
	v_mov_b32_e32 v72, v123
	v_mov_b32_e32 v119, v123
	v_mov_b32_e32 v118, v123
	v_mov_b32_e32 v117, v123
	v_mov_b32_e32 v116, v123
	v_mov_b32_e32 v115, v123
	v_mov_b32_e32 v114, v123
	v_mov_b32_e32 v113, v123
	v_mov_b32_e32 v112, v123
	v_mov_b32_e32 v103, v123
	v_mov_b32_e32 v102, v123
	v_mov_b32_e32 v101, v123
	v_mov_b32_e32 v100, v123
	v_mov_b32_e32 v99, v123
	v_mov_b32_e32 v98, v123
	v_mov_b32_e32 v97, v123
	v_mov_b32_e32 v96, v123
	v_mov_b32_e32 v87, v123
	v_mov_b32_e32 v86, v123
	v_mov_b32_e32 v85, v123
	v_mov_b32_e32 v84, v123
	v_mov_b32_e32 v83, v123
	v_mov_b32_e32 v82, v123
	v_mov_b32_e32 v81, v123
	v_mov_b32_e32 v80, v123
	v_mov_b32_e32 v71, v123
	v_mov_b32_e32 v70, v123
	v_mov_b32_e32 v69, v123
	v_mov_b32_e32 v68, v123
	v_mov_b32_e32 v67, v123
	v_mov_b32_e32 v66, v123
	v_mov_b32_e32 v65, v123
	v_mov_b32_e32 v64, v123
	v_mov_b32_e32 v63, v123
	v_mov_b32_e32 v62, v123
	v_mov_b32_e32 v61, v123
	v_mov_b32_e32 v60, v123
	v_mov_b32_e32 v59, v123
	v_mov_b32_e32 v58, v123
	v_mov_b32_e32 v57, v123
	v_mov_b32_e32 v56, v123
	v_mov_b32_e32 v47, v123
	v_mov_b32_e32 v46, v123
	v_mov_b32_e32 v45, v123
	v_mov_b32_e32 v44, v123
	v_mov_b32_e32 v43, v123
	v_mov_b32_e32 v42, v123
	v_mov_b32_e32 v41, v123
	v_mov_b32_e32 v40, v123
	v_mov_b32_e32 v31, v123
	v_mov_b32_e32 v30, v123
	v_mov_b32_e32 v29, v123
	v_mov_b32_e32 v28, v123
	v_mov_b32_e32 v27, v123
	v_mov_b32_e32 v26, v123
	v_mov_b32_e32 v25, v123
	v_mov_b32_e32 v24, v123
	v_mov_b32_e32 v15, v123
	v_mov_b32_e32 v14, v123
	v_mov_b32_e32 v13, v123
	v_mov_b32_e32 v12, v123
	v_mov_b32_e32 v11, v123
	v_mov_b32_e32 v10, v123
	v_mov_b32_e32 v9, v123
	v_mov_b32_e32 v8, v123
	v_mov_b32_e32 v55, v123
	v_mov_b32_e32 v54, v123
	v_mov_b32_e32 v53, v123
	v_mov_b32_e32 v52, v123
	v_mov_b32_e32 v51, v123
	v_mov_b32_e32 v50, v123
	v_mov_b32_e32 v49, v123
	v_mov_b32_e32 v48, v123
	v_mov_b32_e32 v39, v123
	v_mov_b32_e32 v38, v123
	v_mov_b32_e32 v37, v123
	v_mov_b32_e32 v36, v123
	v_mov_b32_e32 v35, v123
	v_mov_b32_e32 v34, v123
	v_mov_b32_e32 v33, v123
	v_mov_b32_e32 v32, v123
	v_mov_b32_e32 v23, v123
	v_mov_b32_e32 v22, v123
	v_mov_b32_e32 v21, v123
	v_mov_b32_e32 v20, v123
	v_mov_b32_e32 v19, v123
	v_mov_b32_e32 v18, v123
	v_mov_b32_e32 v17, v123
	v_mov_b32_e32 v16, v123
	v_mov_b32_e32 v7, v123
	v_mov_b32_e32 v6, v123
	v_mov_b32_e32 v5, v123
	v_mov_b32_e32 v4, v123
	v_mov_b32_e32 v3, v123
	v_mov_b32_e32 v2, v123
	v_mov_b32_e32 v1, v123
	v_mov_b32_e32 v0, v123
	s_cbranch_vccnz .LBB0_1539
	s_and_b64 s[6:7], s[6:7], exec
	s_cselect_b32 s19, s23, s3
	s_cselect_b32 s48, s22, s2
	s_add_u32 s6, s2, 0x40080
	s_addc_u32 s7, s3, 0
	s_add_u32 s24, s24, 0x100
	v_mov_b32_e32 v0, 0
	s_addc_u32 s25, s25, 0
	s_mov_b32 s2, 0
	v_mov_b32_e32 v1, v0
	v_mov_b32_e32 v2, v0
	v_mov_b32_e32 v3, v0
	v_mov_b32_e32 v4, v0
	v_mov_b32_e32 v5, v0
	v_mov_b32_e32 v6, v0
	v_mov_b32_e32 v7, v0
	v_mov_b32_e32 v16, v0
	v_mov_b32_e32 v17, v0
	v_mov_b32_e32 v18, v0
	v_mov_b32_e32 v19, v0
	v_mov_b32_e32 v20, v0
	v_mov_b32_e32 v21, v0
	v_mov_b32_e32 v22, v0
	v_mov_b32_e32 v23, v0
	v_mov_b32_e32 v32, v0
	v_mov_b32_e32 v33, v0
	v_mov_b32_e32 v34, v0
	v_mov_b32_e32 v35, v0
	v_mov_b32_e32 v36, v0
	v_mov_b32_e32 v37, v0
	v_mov_b32_e32 v38, v0
	v_mov_b32_e32 v39, v0
	v_mov_b32_e32 v48, v0
	v_mov_b32_e32 v49, v0
	v_mov_b32_e32 v50, v0
	v_mov_b32_e32 v51, v0
	v_mov_b32_e32 v52, v0
	v_mov_b32_e32 v53, v0
	v_mov_b32_e32 v54, v0
	v_mov_b32_e32 v55, v0
	v_mov_b32_e32 v8, v0
	v_mov_b32_e32 v9, v0
	v_mov_b32_e32 v10, v0
	v_mov_b32_e32 v11, v0
	v_mov_b32_e32 v12, v0
	v_mov_b32_e32 v13, v0
	v_mov_b32_e32 v14, v0
	v_mov_b32_e32 v15, v0
	v_mov_b32_e32 v24, v0
	v_mov_b32_e32 v25, v0
	v_mov_b32_e32 v26, v0
	v_mov_b32_e32 v27, v0
	v_mov_b32_e32 v28, v0
	v_mov_b32_e32 v29, v0
	v_mov_b32_e32 v30, v0
	v_mov_b32_e32 v31, v0
	v_mov_b32_e32 v40, v0
	v_mov_b32_e32 v41, v0
	v_mov_b32_e32 v42, v0
	v_mov_b32_e32 v43, v0
	v_mov_b32_e32 v44, v0
	v_mov_b32_e32 v45, v0
	v_mov_b32_e32 v46, v0
	v_mov_b32_e32 v47, v0
	v_mov_b32_e32 v56, v0
	v_mov_b32_e32 v57, v0
	v_mov_b32_e32 v58, v0
	v_mov_b32_e32 v59, v0
	v_mov_b32_e32 v60, v0
	v_mov_b32_e32 v61, v0
	v_mov_b32_e32 v62, v0
	v_mov_b32_e32 v63, v0
	v_mov_b32_e32 v64, v0
	v_mov_b32_e32 v65, v0
	v_mov_b32_e32 v66, v0
	v_mov_b32_e32 v67, v0
	v_mov_b32_e32 v68, v0
	v_mov_b32_e32 v69, v0
	v_mov_b32_e32 v70, v0
	v_mov_b32_e32 v71, v0
	v_mov_b32_e32 v80, v0
	v_mov_b32_e32 v81, v0
	v_mov_b32_e32 v82, v0
	v_mov_b32_e32 v83, v0
	v_mov_b32_e32 v84, v0
	v_mov_b32_e32 v85, v0
	v_mov_b32_e32 v86, v0
	v_mov_b32_e32 v87, v0
	v_mov_b32_e32 v96, v0
	v_mov_b32_e32 v97, v0
	v_mov_b32_e32 v98, v0
	v_mov_b32_e32 v99, v0
	v_mov_b32_e32 v100, v0
	v_mov_b32_e32 v101, v0
	v_mov_b32_e32 v102, v0
	v_mov_b32_e32 v103, v0
	v_mov_b32_e32 v112, v0
	v_mov_b32_e32 v113, v0
	v_mov_b32_e32 v114, v0
	v_mov_b32_e32 v115, v0
	v_mov_b32_e32 v116, v0
	v_mov_b32_e32 v117, v0
	v_mov_b32_e32 v118, v0
	v_mov_b32_e32 v119, v0
	v_mov_b32_e32 v72, v0
	v_mov_b32_e32 v73, v0
	v_mov_b32_e32 v74, v0
	v_mov_b32_e32 v75, v0
	v_mov_b32_e32 v76, v0
	v_mov_b32_e32 v77, v0
	v_mov_b32_e32 v78, v0
	v_mov_b32_e32 v79, v0
	v_mov_b32_e32 v88, v0
	v_mov_b32_e32 v89, v0
	v_mov_b32_e32 v90, v0
	v_mov_b32_e32 v91, v0
	v_mov_b32_e32 v92, v0
	v_mov_b32_e32 v93, v0
	v_mov_b32_e32 v94, v0
	v_mov_b32_e32 v95, v0
	v_mov_b32_e32 v104, v0
	v_mov_b32_e32 v105, v0
	v_mov_b32_e32 v106, v0
	v_mov_b32_e32 v107, v0
	v_mov_b32_e32 v108, v0
	v_mov_b32_e32 v109, v0
	v_mov_b32_e32 v110, v0
	v_mov_b32_e32 v111, v0
	v_mov_b32_e32 v124, v0
	v_mov_b32_e32 v125, v0
	v_mov_b32_e32 v126, v0
	v_mov_b32_e32 v127, v0
	v_mov_b32_e32 v120, v0
	v_mov_b32_e32 v121, v0
	v_mov_b32_e32 v122, v0
	v_mov_b32_e32 v123, v0
	.p2align	6

.LBB0_1614:
	v_mov_b32_e32 v143, 0
	s_andn2_b64 vcc, exec, s[12:13]
	v_mov_b32_e32 v142, v143
	v_mov_b32_e32 v141, v143
	v_mov_b32_e32 v140, v143
	v_mov_b32_e32 v139, v143
	v_mov_b32_e32 v138, v143
	v_mov_b32_e32 v137, v143
	v_mov_b32_e32 v136, v143
	v_mov_b32_e32 v127, v143
	v_mov_b32_e32 v126, v143
	v_mov_b32_e32 v125, v143
	v_mov_b32_e32 v124, v143
	v_mov_b32_e32 v123, v143
	v_mov_b32_e32 v122, v143
	v_mov_b32_e32 v121, v143
	v_mov_b32_e32 v120, v143
	v_mov_b32_e32 v111, v143
	v_mov_b32_e32 v110, v143
	v_mov_b32_e32 v109, v143
	v_mov_b32_e32 v108, v143
	v_mov_b32_e32 v107, v143
	v_mov_b32_e32 v106, v143
	v_mov_b32_e32 v105, v143
	v_mov_b32_e32 v104, v143
	v_mov_b32_e32 v95, v143
	v_mov_b32_e32 v94, v143
	v_mov_b32_e32 v93, v143
	v_mov_b32_e32 v92, v143
	v_mov_b32_e32 v91, v143
	v_mov_b32_e32 v90, v143
	v_mov_b32_e32 v89, v143
	v_mov_b32_e32 v88, v143
	v_mov_b32_e32 v135, v143
	v_mov_b32_e32 v134, v143
	v_mov_b32_e32 v133, v143
	v_mov_b32_e32 v132, v143
	v_mov_b32_e32 v131, v143
	v_mov_b32_e32 v130, v143
	v_mov_b32_e32 v129, v143
	v_mov_b32_e32 v128, v143
	v_mov_b32_e32 v119, v143
	v_mov_b32_e32 v118, v143
	v_mov_b32_e32 v117, v143
	v_mov_b32_e32 v116, v143
	v_mov_b32_e32 v115, v143
	v_mov_b32_e32 v114, v143
	v_mov_b32_e32 v113, v143
	v_mov_b32_e32 v112, v143
	v_mov_b32_e32 v103, v143
	v_mov_b32_e32 v102, v143
	v_mov_b32_e32 v101, v143
	v_mov_b32_e32 v100, v143
	v_mov_b32_e32 v99, v143
	v_mov_b32_e32 v98, v143
	v_mov_b32_e32 v97, v143
	v_mov_b32_e32 v96, v143
	v_mov_b32_e32 v87, v143
	v_mov_b32_e32 v86, v143
	v_mov_b32_e32 v85, v143
	v_mov_b32_e32 v84, v143
	v_mov_b32_e32 v83, v143
	v_mov_b32_e32 v82, v143
	v_mov_b32_e32 v81, v143
	v_mov_b32_e32 v80, v143
	v_mov_b32_e32 v63, v143
	v_mov_b32_e32 v62, v143
	v_mov_b32_e32 v61, v143
	v_mov_b32_e32 v60, v143
	v_mov_b32_e32 v59, v143
	v_mov_b32_e32 v58, v143
	v_mov_b32_e32 v57, v143
	v_mov_b32_e32 v56, v143
	v_mov_b32_e32 v47, v143
	v_mov_b32_e32 v46, v143
	v_mov_b32_e32 v45, v143
	v_mov_b32_e32 v44, v143
	v_mov_b32_e32 v43, v143
	v_mov_b32_e32 v42, v143
	v_mov_b32_e32 v41, v143
	v_mov_b32_e32 v40, v143
	v_mov_b32_e32 v31, v143
	v_mov_b32_e32 v30, v143
	v_mov_b32_e32 v29, v143
	v_mov_b32_e32 v28, v143
	v_mov_b32_e32 v27, v143
	v_mov_b32_e32 v26, v143
	v_mov_b32_e32 v25, v143
	v_mov_b32_e32 v24, v143
	v_mov_b32_e32 v15, v143
	v_mov_b32_e32 v14, v143
	v_mov_b32_e32 v13, v143
	v_mov_b32_e32 v12, v143
	v_mov_b32_e32 v11, v143
	v_mov_b32_e32 v10, v143
	v_mov_b32_e32 v9, v143
	v_mov_b32_e32 v8, v143
	v_mov_b32_e32 v55, v143
	v_mov_b32_e32 v54, v143
	v_mov_b32_e32 v53, v143
	v_mov_b32_e32 v52, v143
	v_mov_b32_e32 v51, v143
	v_mov_b32_e32 v50, v143
	v_mov_b32_e32 v49, v143
	v_mov_b32_e32 v48, v143
	v_mov_b32_e32 v39, v143
	v_mov_b32_e32 v38, v143
	v_mov_b32_e32 v37, v143
	v_mov_b32_e32 v36, v143
	v_mov_b32_e32 v35, v143
	v_mov_b32_e32 v34, v143
	v_mov_b32_e32 v33, v143
	v_mov_b32_e32 v32, v143
	v_mov_b32_e32 v23, v143
	v_mov_b32_e32 v22, v143
	v_mov_b32_e32 v21, v143
	v_mov_b32_e32 v20, v143
	v_mov_b32_e32 v19, v143
	v_mov_b32_e32 v18, v143
	v_mov_b32_e32 v17, v143
	v_mov_b32_e32 v16, v143
	v_mov_b32_e32 v7, v143
	v_mov_b32_e32 v6, v143
	v_mov_b32_e32 v5, v143
	v_mov_b32_e32 v4, v143
	v_mov_b32_e32 v3, v143
	v_mov_b32_e32 v2, v143
	v_mov_b32_e32 v1, v143
	v_mov_b32_e32 v0, v143
	s_cbranch_vccnz .LBB0_1617
	s_add_u32 s46, s20, 0x100
	v_mov_b32_e32 v0, 0
	s_addc_u32 s47, s21, 0
	s_mov_b32 s20, 0
	v_mov_b32_e32 v1, v0
	v_mov_b32_e32 v2, v0
	v_mov_b32_e32 v3, v0
	v_mov_b32_e32 v4, v0
	v_mov_b32_e32 v5, v0
	v_mov_b32_e32 v6, v0
	v_mov_b32_e32 v7, v0
	v_mov_b32_e32 v16, v0
	v_mov_b32_e32 v17, v0
	v_mov_b32_e32 v18, v0
	v_mov_b32_e32 v19, v0
	v_mov_b32_e32 v20, v0
	v_mov_b32_e32 v21, v0
	v_mov_b32_e32 v22, v0
	v_mov_b32_e32 v23, v0
	v_mov_b32_e32 v32, v0
	v_mov_b32_e32 v33, v0
	v_mov_b32_e32 v34, v0
	v_mov_b32_e32 v35, v0
	v_mov_b32_e32 v36, v0
	v_mov_b32_e32 v37, v0
	v_mov_b32_e32 v38, v0
	v_mov_b32_e32 v39, v0
	v_mov_b32_e32 v48, v0
	v_mov_b32_e32 v49, v0
	v_mov_b32_e32 v50, v0
	v_mov_b32_e32 v51, v0
	v_mov_b32_e32 v52, v0
	v_mov_b32_e32 v53, v0
	v_mov_b32_e32 v54, v0
	v_mov_b32_e32 v55, v0
	v_mov_b32_e32 v8, v0
	v_mov_b32_e32 v9, v0
	v_mov_b32_e32 v10, v0
	v_mov_b32_e32 v11, v0
	v_mov_b32_e32 v12, v0
	v_mov_b32_e32 v13, v0
	v_mov_b32_e32 v14, v0
	v_mov_b32_e32 v15, v0
	v_mov_b32_e32 v24, v0
	v_mov_b32_e32 v25, v0
	v_mov_b32_e32 v26, v0
	v_mov_b32_e32 v27, v0
	v_mov_b32_e32 v28, v0
	v_mov_b32_e32 v29, v0
	v_mov_b32_e32 v30, v0
	v_mov_b32_e32 v31, v0
	v_mov_b32_e32 v40, v0
	v_mov_b32_e32 v41, v0
	v_mov_b32_e32 v42, v0
	v_mov_b32_e32 v43, v0
	v_mov_b32_e32 v44, v0
	v_mov_b32_e32 v45, v0
	v_mov_b32_e32 v46, v0
	v_mov_b32_e32 v47, v0
	v_mov_b32_e32 v56, v0
	v_mov_b32_e32 v57, v0
	v_mov_b32_e32 v58, v0
	v_mov_b32_e32 v59, v0
	v_mov_b32_e32 v60, v0
	v_mov_b32_e32 v61, v0
	v_mov_b32_e32 v62, v0
	v_mov_b32_e32 v63, v0
	v_mov_b32_e32 v80, v0
	v_mov_b32_e32 v81, v0
	v_mov_b32_e32 v82, v0
	v_mov_b32_e32 v83, v0
	v_mov_b32_e32 v84, v0
	v_mov_b32_e32 v85, v0
	v_mov_b32_e32 v86, v0
	v_mov_b32_e32 v87, v0
	v_mov_b32_e32 v96, v0
	v_mov_b32_e32 v97, v0
	v_mov_b32_e32 v98, v0
	v_mov_b32_e32 v99, v0
	v_mov_b32_e32 v100, v0
	v_mov_b32_e32 v101, v0
	v_mov_b32_e32 v102, v0
	v_mov_b32_e32 v103, v0
	v_mov_b32_e32 v112, v0
	v_mov_b32_e32 v113, v0
	v_mov_b32_e32 v114, v0
	v_mov_b32_e32 v115, v0
	v_mov_b32_e32 v116, v0
	v_mov_b32_e32 v117, v0
	v_mov_b32_e32 v118, v0
	v_mov_b32_e32 v119, v0
	v_mov_b32_e32 v128, v0
	v_mov_b32_e32 v129, v0
	v_mov_b32_e32 v130, v0
	v_mov_b32_e32 v131, v0
	v_mov_b32_e32 v132, v0
	v_mov_b32_e32 v133, v0
	v_mov_b32_e32 v134, v0
	v_mov_b32_e32 v135, v0
	v_mov_b32_e32 v88, v0
	v_mov_b32_e32 v89, v0
	v_mov_b32_e32 v90, v0
	v_mov_b32_e32 v91, v0
	v_mov_b32_e32 v92, v0
	v_mov_b32_e32 v93, v0
	v_mov_b32_e32 v94, v0
	v_mov_b32_e32 v95, v0
	v_mov_b32_e32 v104, v0
	v_mov_b32_e32 v105, v0
	v_mov_b32_e32 v106, v0
	v_mov_b32_e32 v107, v0
	v_mov_b32_e32 v108, v0
	v_mov_b32_e32 v109, v0
	v_mov_b32_e32 v110, v0
	v_mov_b32_e32 v111, v0
	v_mov_b32_e32 v120, v0
	v_mov_b32_e32 v121, v0
	v_mov_b32_e32 v122, v0
	v_mov_b32_e32 v123, v0
	v_mov_b32_e32 v124, v0
	v_mov_b32_e32 v125, v0
	v_mov_b32_e32 v126, v0
	v_mov_b32_e32 v127, v0
	v_mov_b32_e32 v136, v0
	v_mov_b32_e32 v137, v0
	v_mov_b32_e32 v138, v0
	v_mov_b32_e32 v139, v0
	v_mov_b32_e32 v140, v0
	v_mov_b32_e32 v141, v0
	v_mov_b32_e32 v142, v0
	v_mov_b32_e32 v143, v0
	.p2align	6
